# bh2 + grid barrier pre-flush: each XCD's first arriver issues a non-blocking L2 write-back while it waits
# baseline (speedup 1.0000x reference)
; __device__ __forceinline__ unsigned xb_ld(unsigned* p)              { return __hip_atomic_load(p, __ATOMIC_RELAXED, __HIP_MEMORY_SCOPE_AGENT); }
; __device__ __forceinline__ unsigned xb_add(unsigned* p, unsigned v) { return __hip_atomic_fetch_add(p, v, __ATOMIC_RELAXED, __HIP_MEMORY_SCOPE_AGENT); }
; #define XB_SPIN(cond, bar) do { unsigned _sp = 0; while (cond) { __builtin_amdgcn_s_sleep(1); \
;     if ((++_sp & 255u) == 0u) { if (xb_ld(&(bar)[XB_TMO])) break; if (_sp > XB_SPIN_CAP) { atomicAdd(&(bar)[XB_TMO], 1u); break; } } } } while (0)
; __device__ __forceinline__ void xcd_barrier(const XcdBarrier& b, int tid) {
;     ...
;         const unsigned old = xb_add(&bar[XB_XSUB(b.x)], 1u);
;         const unsigned gen = old / nloc;
;         if (old + 1u == (gen + 1u) * nloc) {
;             __builtin_amdgcn_fence(__ATOMIC_RELEASE, "agent");
;             asm volatile("s_waitcnt vmcnt(0)" ::: "memory");
;             const unsigned og = xb_add(&bar[XB_TOP], 1u);
;             const unsigned tg = og / nx;
;             if (og + 1u == (tg + 1u) * nx) xb_add(&bar[XB_TOPGEN], 1u);
;             else XB_SPIN(xb_ld(&bar[XB_TOPGEN]) == tg, bar);
;             __builtin_amdgcn_fence(__ATOMIC_ACQUIRE, "agent");
;             xb_add(&bar[XB_XGEN(b.x)], 1u);
;             asm volatile("s_waitcnt vmcnt(0)" ::: "memory");
;         } else {
;             XB_SPIN(xb_ld(&bar[XB_XGEN(b.x)]) == gen, bar);
.LBB0_105:
	s_or_b64 exec, exec, s[12:13]
	v_cvt_f32_u32_e32 v5, v3
	s_waitcnt vmcnt(0)
	buffer_inv sc1
	v_readfirstlane_b32 s3, v4
	v_sub_u32_e32 v4, 0, v3
	v_rcp_iflag_f32_e32 v5, v5
	v_add_u32_e32 v6, s3, v2
	v_mul_f32_e32 v5, 0x4f7ffffe, v5
	v_cvt_u32_f32_e32 v5, v5
	v_mul_lo_u32 v2, v4, v5
	v_mul_hi_u32 v2, v5, v2
	v_add_u32_e32 v2, v5, v2
	v_mul_hi_u32 v2, v6, v2
	v_mul_lo_u32 v4, v2, v3
	v_sub_u32_e32 v4, v6, v4
	v_add_u32_e32 v5, 1, v2
	v_cmp_ge_u32_e32 vcc, v4, v3
	s_nop 1
	v_cndmask_b32_e32 v2, v2, v5, vcc
	v_sub_u32_e32 v5, v4, v3
	v_cndmask_b32_e32 v4, v4, v5, vcc
	v_add_u32_e32 v5, 1, v2
	v_cmp_ge_u32_e32 vcc, v4, v3
	v_add_u32_e32 v4, 1, v6
	s_nop 0
	v_cndmask_b32_e32 v2, v2, v5, vcc
	v_mul_lo_u32 v5, v3, v2
	v_add_u32_e32 v3, v5, v3
	v_cmp_ne_u32_e32 vcc, v4, v3
	s_and_saveexec_b64 s[10:11], vcc
	s_xor_b64 s[10:11], exec, s[10:11]
	s_cbranch_execz .LBB0_119
	s_waitcnt lgkmcnt(0)
	v_sub_u32_e32 v7, v6, v5
	v_and_b32_e32 v7, 65535, v7
	v_cmp_eq_u32_e32 vcc, 0, v7
	s_cbranch_vccz .Lpf_skip_0
	buffer_wbl2 sc1
.Lpf_skip_0:
	v_mov_b32_e32 v1, 0x3100
	global_load_dword v1, v1, s[6:7] offset:1024 sc1
	s_add_u32 s14, s6, 0x3500
	s_addc_u32 s15, s7, 0
	s_waitcnt vmcnt(0)
	v_cmp_eq_u32_e32 vcc, v1, v2
	s_and_saveexec_b64 s[12:13], vcc
	s_cbranch_execz .LBB0_118
	s_mov_b32 s3, 1
	s_mov_b64 s[16:17], 0
	v_mov_b32_e32 v1, 0
	s_branch .LBB0_109

; __device__ __forceinline__ unsigned xb_ld(unsigned* p)              { return __hip_atomic_load(p, __ATOMIC_RELAXED, __HIP_MEMORY_SCOPE_AGENT); }
; __device__ __forceinline__ unsigned xb_add(unsigned* p, unsigned v) { return __hip_atomic_fetch_add(p, v, __ATOMIC_RELAXED, __HIP_MEMORY_SCOPE_AGENT); }
; #define XB_SPIN(cond, bar) do { unsigned _sp = 0; while (cond) { __builtin_amdgcn_s_sleep(1); \
;     if ((++_sp & 255u) == 0u) { if (xb_ld(&(bar)[XB_TMO])) break; if (_sp > XB_SPIN_CAP) { atomicAdd(&(bar)[XB_TMO], 1u); break; } } } } while (0)
; __device__ __forceinline__ void xcd_barrier(const XcdBarrier& b, int tid) {
;     ...
;         const unsigned old = xb_add(&bar[XB_XSUB(b.x)], 1u);
;         const unsigned gen = old / nloc;
;         if (old + 1u == (gen + 1u) * nloc) {
;             __builtin_amdgcn_fence(__ATOMIC_RELEASE, "agent");
;             asm volatile("s_waitcnt vmcnt(0)" ::: "memory");
;             const unsigned og = xb_add(&bar[XB_TOP], 1u);
;             const unsigned tg = og / nx;
;             if (og + 1u == (tg + 1u) * nx) xb_add(&bar[XB_TOPGEN], 1u);
;             else XB_SPIN(xb_ld(&bar[XB_TOPGEN]) == tg, bar);
;             __builtin_amdgcn_fence(__ATOMIC_ACQUIRE, "agent");
;             xb_add(&bar[XB_XGEN(b.x)], 1u);
;             asm volatile("s_waitcnt vmcnt(0)" ::: "memory");
;         } else {
;             XB_SPIN(xb_ld(&bar[XB_XGEN(b.x)]) == gen, bar);
.LBB0_378:
	s_or_b64 exec, exec, s[10:11]
	v_cvt_f32_u32_e32 v5, v3
	s_waitcnt vmcnt(0)
	buffer_inv sc1
	v_readfirstlane_b32 s3, v4
	v_sub_u32_e32 v4, 0, v3
	v_rcp_iflag_f32_e32 v5, v5
	v_add_u32_e32 v6, s3, v2
	v_mul_f32_e32 v5, 0x4f7ffffe, v5
	v_cvt_u32_f32_e32 v5, v5
	v_mul_lo_u32 v2, v4, v5
	v_mul_hi_u32 v2, v5, v2
	v_add_u32_e32 v2, v5, v2
	v_mul_hi_u32 v2, v6, v2
	v_mul_lo_u32 v4, v2, v3
	v_sub_u32_e32 v4, v6, v4
	v_add_u32_e32 v5, 1, v2
	v_cmp_ge_u32_e32 vcc, v4, v3
	s_nop 1
	v_cndmask_b32_e32 v2, v2, v5, vcc
	v_sub_u32_e32 v5, v4, v3
	v_cndmask_b32_e32 v4, v4, v5, vcc
	v_add_u32_e32 v5, 1, v2
	v_cmp_ge_u32_e32 vcc, v4, v3
	v_add_u32_e32 v4, 1, v6
	s_nop 0
	v_cndmask_b32_e32 v2, v2, v5, vcc
	v_mul_lo_u32 v5, v3, v2
	v_add_u32_e32 v3, v5, v3
	v_cmp_ne_u32_e32 vcc, v4, v3
	s_and_saveexec_b64 s[8:9], vcc
	s_xor_b64 s[8:9], exec, s[8:9]
	s_cbranch_execz .LBB0_392
	s_waitcnt lgkmcnt(0)
	v_sub_u32_e32 v7, v6, v5
	v_and_b32_e32 v7, 65535, v7
	v_cmp_eq_u32_e32 vcc, 0, v7
	s_cbranch_vccz .Lpf_skip_2
	buffer_wbl2 sc1
.Lpf_skip_2:
	v_mov_b32_e32 v1, 0x3100
	global_load_dword v1, v1, s[4:5] offset:1024 sc1
	s_add_u32 s12, s4, 0x3500
	s_addc_u32 s13, s5, 0
	s_waitcnt vmcnt(0)
	v_cmp_eq_u32_e32 vcc, v1, v2
	s_and_saveexec_b64 s[10:11], vcc
	s_cbranch_execz .LBB0_391
	s_mov_b32 s3, 1
	s_mov_b64 s[14:15], 0
	v_mov_b32_e32 v1, 0
	s_branch .LBB0_382
